# speedup vs baseline: 1.0047x; 1.0028x over previous
;   __device__ __forceinline__ u16* hbuf() const { return (u16*)(ws + 57 * MB); }
; #define WAIT_V(n) asm volatile("s_waitcnt vmcnt(%0)" ::"n"(n) : "memory")
; template <int EPI> ...
;     ...
;     const u16 *Ab2 = Ab, *Bb2 = Bb;
;     if (have2) {
;       const int pass2 = (NPASS == 2) ? (job & 1) : 0;
;       Ab2 = A + (long)(pm2 * 256) * lda + pass2 * 512;
;       Bb2 = (pass2 ? Bt2 : Bt) + (long)(pn2 * 256) * K;
;     ...
;       STAGE_Bm(1, 0, Bb, 1); STAGE_A(1, 0, Ab, 1); STAGE_Bm(1, 1, Bb, 1);
;       WAIT_V(6); BAR8;
; #pragma unroll 1
;       for (int t0_ = 0; t0_ < nt - 2; t0_ += 2) {
;         if constexpr (EPI == EPI_M0) {
;           if (t0_ == 8) {
;             int tid_s = tid;
;             asm volatile("" : "+v"(tid_s));
;             const int wid = tid_s >> 6, lane = tid_s & 63, wr = wid >> 2, wc = wid & 3, fr = lane & 15, fq = lane >> 4;
;             char* wsn = shm + 131072 + wid * 4096;
;             u16* sout = p.hbuf() + (long)(pm * 256 + wr * 128 + (lane >> 3)) * DM + pn * 256 + wc * 64 + (lane & 7) * 8;
; #pragma unroll
;             for (int qd = 0; qd < 4; ++qd) {
; #pragma unroll
;               for (int mm = 0; mm < 2; ++mm)
; #pragma unroll
;                 for (int n = 0; n < 4; ++n) {
;                   const f32x4 v = acc[qd * 2 + mm][n];
;                   u32x2 o = {pack2(v[0], v[1]), pack2(v[2], v[3])};
;                   *(u32x2*)(wsn + (mm * 16 + fr) * 128 + (((n * 2 + (fq >> 1)) ^ (fr & 7)) << 4) + (fq & 1) * 8) = o;
;                 }
;               asm volatile("s_waitcnt lgkmcnt(0)" ::: "memory");
; #pragma unroll
;               for (int i = 0; i < 4; ++i) {
;                 const u32x4 d = *(const u32x4*)(wsn + (i * 8 + (lane >> 3)) * 128 + (((lane & 7) ^ ((lane >> 3) & 7)) << 4));
;                 *(u32x4*)(sout + (long)(qd * 32 + i * 8) * DM) = d;
;               }
;               asm volatile("s_waitcnt lgkmcnt(0)" ::: "memory");
;             }
;           }
;         }
;         int t = t0_;
;         asm volatile("" : "+s"(t));
;         LDB8(B0, 0, 0); SCHED8; LDA8(At, 0, 0); STAGE_A(1, 1, Ab, t + 1);
;         WAIT_L(8); BAR8; WAIT_L(0); MMA8(0, 0, At, B0); BAR8; SCHED8;
;         LDB8(B1, 0, 1); STAGE_Bm(0, 0, Bb, t + 2);
;         BAR8; WAIT_L(0); MMA8(0, 1, At, B1); BAR8;
;         LDA8(At, 0, 1); STAGE_A(0, 0, Ab, t + 2);
;         BAR8; WAIT_L(0); MMA8(1, 0, At, B0); BAR8; SCHED8;
.LBB0_683:
	v_lshl_add_u64 v[172:173], s[22:23], 0, v[4:5]
	v_lshl_add_u64 v[170:171], s[24:25], 0, v[0:1]
	s_mov_b64 s[22:23], 0x20000
	v_lshl_add_u64 v[174:175], v[170:171], 0, s[22:23]
	v_lshl_add_u64 v[176:177], v[172:173], 0, s[44:45]
	v_add_u32_e32 v180, 0x10000, v7
	v_add_u32_e32 v181, 0x10000, v153
	v_lshl_add_u64 v[156:157], s[14:15], 0, v[0:1]
	v_lshl_add_u64 v[158:159], s[16:17], 0, v[4:5]
	v_lshl_add_u64 v[182:183], v[156:157], 0, s[22:23]
	v_lshl_add_u64 v[250:251], v[158:159], 0, s[44:45]
	s_mov_b64 s[22:23], 0x80
	s_add_i32 m0, s96, 0x10000
	v_lshl_add_u64 v[178:179], v[170:171], 0, s[22:23]
	global_load_lds_dwordx4 v[178:179], off
	s_add_i32 m0, s96, 0x12000
	v_lshl_add_u64 v[178:179], v[170:171], 0, s[22:23]
	v_lshl_add_u64 v[178:179], v[178:179], 0, s[62:63]
	global_load_lds_dwordx4 v[178:179], off
	s_add_i32 m0, s96, 0x14000
	v_lshl_add_u64 v[178:179], v[174:175], 0, s[22:23]
	global_load_lds_dwordx4 v[178:179], off
	s_add_i32 m0, s96, 0x16000
	v_lshl_add_u64 v[178:179], v[174:175], 0, s[22:23]
	v_lshl_add_u64 v[178:179], v[178:179], 0, s[62:63]
	global_load_lds_dwordx4 v[178:179], off
	s_add_i32 m0, s96, 0x18000
	v_lshl_add_u64 v[178:179], v[172:173], 0, s[22:23]
	global_load_lds_dwordx4 v[178:179], off
	s_add_i32 m0, s96, 0x1a000
	v_lshl_add_u64 v[178:179], v[172:173], 0, s[22:23]
	v_lshl_add_u64 v[178:179], v[178:179], 0, s[62:63]
	global_load_lds_dwordx4 v[178:179], off
	s_add_i32 m0, s96, 0x1c000
	v_lshl_add_u64 v[178:179], v[176:177], 0, s[22:23]
	global_load_lds_dwordx4 v[178:179], off
	s_add_i32 m0, s96, 0x1e000
	v_lshl_add_u64 v[178:179], v[176:177], 0, s[22:23]
	v_lshl_add_u64 v[178:179], v[178:179], 0, s[62:63]
	global_load_lds_dwordx4 v[178:179], off
	ds_read_b128 v[186:189], v153 offset:32768
	ds_read_b128 v[190:193], v153 offset:34816
	ds_read_b128 v[218:221], v7
	ds_read_b128 v[194:197], v153 offset:49152
	ds_read_b128 v[198:201], v153 offset:51200
	ds_read_b128 v[222:225], v7 offset:2048
	ds_read_b128 v[226:229], v7 offset:4096
	ds_read_b128 v[230:233], v7 offset:6144
	ds_read_b128 v[234:237], v7 offset:16384
	s_waitcnt lgkmcnt(4)
	v_mfma_f32_16x16x32_bf16 v[132:135], v[186:189], v[218:221], 0
	v_mfma_f32_16x16x32_bf16 v[124:127], v[190:193], v[218:221], 0
	v_mfma_f32_16x16x32_bf16 v[128:131], v[194:197], v[218:221], 0
	v_mfma_f32_16x16x32_bf16 v[120:123], v[198:201], v[218:221], 0
	ds_read_b128 v[238:241], v7 offset:18432
	ds_read_b128 v[202:205], v153 offset:33792
	s_waitcnt lgkmcnt(5)
	v_mfma_f32_16x16x32_bf16 v[116:119], v[186:189], v[222:225], 0
	v_mfma_f32_16x16x32_bf16 v[108:111], v[190:193], v[222:225], 0
	v_mfma_f32_16x16x32_bf16 v[112:115], v[194:197], v[222:225], 0
	v_mfma_f32_16x16x32_bf16 v[104:107], v[198:201], v[222:225], 0
	ds_read_b128 v[242:245], v7 offset:20480
	ds_read_b128 v[206:209], v153 offset:35840
	s_waitcnt lgkmcnt(6)
	v_mfma_f32_16x16x32_bf16 v[100:103], v[186:189], v[226:229], 0
	v_mfma_f32_16x16x32_bf16 v[92:95], v[190:193], v[226:229], 0
	v_mfma_f32_16x16x32_bf16 v[96:99], v[194:197], v[226:229], 0
	v_mfma_f32_16x16x32_bf16 v[88:91], v[198:201], v[226:229], 0
	ds_read_b128 v[246:249], v7 offset:22528
	ds_read_b128 v[210:213], v153 offset:50176
	s_waitcnt lgkmcnt(7)
	v_mfma_f32_16x16x32_bf16 v[84:87], v[186:189], v[230:233], 0
	v_mfma_f32_16x16x32_bf16 v[76:79], v[190:193], v[230:233], 0
	v_mfma_f32_16x16x32_bf16 v[80:83], v[194:197], v[230:233], 0
	v_mfma_f32_16x16x32_bf16 v[72:75], v[198:201], v[230:233], 0
	ds_read_b128 v[218:221], v7 offset:1024
	ds_read_b128 v[214:217], v153 offset:52224
	s_add_u32 s22, s22, 0x80
	s_waitcnt lgkmcnt(8)
	v_mfma_f32_16x16x32_bf16 v[68:71], v[186:189], v[234:237], 0
	v_mfma_f32_16x16x32_bf16 v[64:67], v[190:193], v[234:237], 0
	v_mfma_f32_16x16x32_bf16 v[60:63], v[194:197], v[234:237], 0
	v_mfma_f32_16x16x32_bf16 v[56:59], v[198:201], v[234:237], 0
	ds_read_b128 v[222:225], v7 offset:3072
	s_waitcnt lgkmcnt(8)
	v_mfma_f32_16x16x32_bf16 v[52:55], v[186:189], v[238:241], 0
	v_mfma_f32_16x16x32_bf16 v[48:51], v[190:193], v[238:241], 0
	v_mfma_f32_16x16x32_bf16 v[44:47], v[194:197], v[238:241], 0
	v_mfma_f32_16x16x32_bf16 v[40:43], v[198:201], v[238:241], 0
	ds_read_b128 v[226:229], v7 offset:5120
	s_waitcnt lgkmcnt(7)
	v_mfma_f32_16x16x32_bf16 v[36:39], v[186:189], v[242:245], 0
	v_mfma_f32_16x16x32_bf16 v[32:35], v[190:193], v[242:245], 0
	v_mfma_f32_16x16x32_bf16 v[28:31], v[194:197], v[242:245], 0
	v_mfma_f32_16x16x32_bf16 v[24:27], v[198:201], v[242:245], 0
	ds_read_b128 v[230:233], v7 offset:7168
	s_waitcnt lgkmcnt(6)
	v_mfma_f32_16x16x32_bf16 v[20:23], v[186:189], v[246:249], 0
	v_mfma_f32_16x16x32_bf16 v[16:19], v[190:193], v[246:249], 0
	v_mfma_f32_16x16x32_bf16 v[12:15], v[194:197], v[246:249], 0
	v_mfma_f32_16x16x32_bf16 v[8:11], v[198:201], v[246:249], 0
	ds_read_b128 v[234:237], v7 offset:17408
	s_waitcnt lgkmcnt(4)
	v_mfma_f32_16x16x32_bf16 v[132:135], v[202:205], v[218:221], v[132:135]
	v_mfma_f32_16x16x32_bf16 v[124:127], v[206:209], v[218:221], v[124:127]
	v_mfma_f32_16x16x32_bf16 v[128:131], v[210:213], v[218:221], v[128:131]
	v_mfma_f32_16x16x32_bf16 v[120:123], v[214:217], v[218:221], v[120:123]
	ds_read_b128 v[238:241], v7 offset:19456
	s_waitcnt lgkmcnt(4)
	v_mfma_f32_16x16x32_bf16 v[116:119], v[202:205], v[222:225], v[116:119]
	v_mfma_f32_16x16x32_bf16 v[108:111], v[206:209], v[222:225], v[108:111]
	v_mfma_f32_16x16x32_bf16 v[112:115], v[210:213], v[222:225], v[112:115]
	v_mfma_f32_16x16x32_bf16 v[104:107], v[214:217], v[222:225], v[104:107]
	ds_read_b128 v[242:245], v7 offset:21504
	s_waitcnt lgkmcnt(4)
	v_mfma_f32_16x16x32_bf16 v[100:103], v[202:205], v[226:229], v[100:103]
	v_mfma_f32_16x16x32_bf16 v[92:95], v[206:209], v[226:229], v[92:95]
	v_mfma_f32_16x16x32_bf16 v[96:99], v[210:213], v[226:229], v[96:99]
	v_mfma_f32_16x16x32_bf16 v[88:91], v[214:217], v[226:229], v[88:91]
	ds_read_b128 v[246:249], v7 offset:23552
	s_waitcnt lgkmcnt(4)
	v_mfma_f32_16x16x32_bf16 v[84:87], v[202:205], v[230:233], v[84:87]
	v_mfma_f32_16x16x32_bf16 v[76:79], v[206:209], v[230:233], v[76:79]
	v_mfma_f32_16x16x32_bf16 v[80:83], v[210:213], v[230:233], v[80:83]
	v_mfma_f32_16x16x32_bf16 v[72:75], v[214:217], v[230:233], v[72:75]
	s_waitcnt vmcnt(0) lgkmcnt(0)
	s_barrier
; template <int EPI> ...
;     ...
;       for (int t0_ = 0; t0_ < nt - 2; t0_ += 2) {
;         if constexpr (EPI == EPI_M0) {
;           if (t0_ == 8) {
;             int tid_s = tid;
;             asm volatile("" : "+v"(tid_s));
;             const int wid = tid_s >> 6, lane = tid_s & 63, wr = wid >> 2, wc = wid & 3, fr = lane & 15, fq = lane >> 4;
;             char* wsn = shm + 131072 + wid * 4096;
;             u16* sout = p.hbuf() + (long)(pm * 256 + wr * 128 + (lane >> 3)) * DM + pn * 256 + wc * 64 + (lane & 7) * 8;
; #pragma unroll
;             for (int qd = 0; qd < 4; ++qd) {
; #pragma unroll
;               for (int mm = 0; mm < 2; ++mm)
; #pragma unroll
;                 for (int n = 0; n < 4; ++n) {
;                   const f32x4 v = acc[qd * 2 + mm][n];
;                   u32x2 o = {pack2(v[0], v[1]), pack2(v[2], v[3])};
;                   *(u32x2*)(wsn + (mm * 16 + fr) * 128 + (((n * 2 + (fq >> 1)) ^ (fr & 7)) << 4) + (fq & 1) * 8) = o;
;                 }
;               asm volatile("s_waitcnt lgkmcnt(0)" ::: "memory");
; #pragma unroll
;               for (int i = 0; i < 4; ++i) {
;                 const u32x4 d = *(const u32x4*)(wsn + (i * 8 + (lane >> 3)) * 128 + (((lane & 7) ^ ((lane >> 3) & 7)) << 4));
;                 *(u32x4*)(sout + (long)(qd * 32 + i * 8) * DM) = d;
;               }
;               asm volatile("s_waitcnt lgkmcnt(0)" ::: "memory");
;             }
;           }
;         }
;         int t = t0_;
;         asm volatile("" : "+s"(t));
;         LDB8(B0, 0, 0); SCHED8; LDA8(At, 0, 0); STAGE_A(1, 1, Ab, t + 1);
;         WAIT_L(8); BAR8; WAIT_L(0); MMA8(0, 0, At, B0); BAR8; SCHED8;
;         LDB8(B1, 0, 1); STAGE_Bm(0, 0, Bb, t + 2);
;         BAR8; WAIT_L(0); MMA8(0, 1, At, B1); BAR8;
;         LDA8(At, 0, 1); STAGE_A(0, 0, Ab, t + 2);
;         BAR8; WAIT_L(0); MMA8(1, 0, At, B0); BAR8; SCHED8;
;         STAGE_Bm(0, 1, Bb, t + 2);
;         WAIT_V(6); BAR8; MMA8(1, 1, At, B1); BAR8;
;         LDB8(B0, 1, 0); SCHED8; LDA8(At, 1, 0); STAGE_A(0, 1, Ab, t + 2);
;         WAIT_L(8); BAR8; WAIT_L(0); MMA8(0, 0, At, B0); BAR8; SCHED8;
;         LDB8(B1, 1, 1); STAGE_Bm(1, 0, Bb, t + 3);
;         BAR8; WAIT_L(0); MMA8(0, 1, At, B1); BAR8;
;         LDA8(At, 1, 1); STAGE_A(1, 0, Ab, t + 3);
;         BAR8; WAIT_L(0); MMA8(1, 0, At, B0); BAR8; SCHED8;
;         STAGE_Bm(1, 1, Bb, t + 3);
	v_mfma_f32_16x16x32_bf16 v[68:71], v[202:205], v[234:237], v[68:71]
	v_mfma_f32_16x16x32_bf16 v[64:67], v[206:209], v[234:237], v[64:67]
	v_mfma_f32_16x16x32_bf16 v[60:63], v[210:213], v[234:237], v[60:63]
	v_mfma_f32_16x16x32_bf16 v[56:59], v[214:217], v[234:237], v[56:59]
	ds_read_b128 v[186:189], v181 offset:32768
	ds_read_b128 v[190:193], v181 offset:34816
	ds_read_b128 v[218:221], v180
	s_mov_b32 m0, s96
	v_lshl_add_u64 v[178:179], v[170:171], 0, s[22:23]
	global_load_lds_dwordx4 v[178:179], off
	s_waitcnt lgkmcnt(5)
	v_mfma_f32_16x16x32_bf16 v[52:55], v[202:205], v[238:241], v[52:55]
	v_mfma_f32_16x16x32_bf16 v[48:51], v[206:209], v[238:241], v[48:51]
	v_mfma_f32_16x16x32_bf16 v[44:47], v[210:213], v[238:241], v[44:47]
	v_mfma_f32_16x16x32_bf16 v[40:43], v[214:217], v[238:241], v[40:43]
	ds_read_b128 v[194:197], v181 offset:49152
	ds_read_b128 v[198:201], v181 offset:51200
	ds_read_b128 v[222:225], v180 offset:2048
	s_add_i32 m0, s96, 0x2000
	v_lshl_add_u64 v[178:179], v[170:171], 0, s[22:23]
	v_lshl_add_u64 v[178:179], v[178:179], 0, s[62:63]
	global_load_lds_dwordx4 v[178:179], off
	s_waitcnt lgkmcnt(7)
	v_mfma_f32_16x16x32_bf16 v[36:39], v[202:205], v[242:245], v[36:39]
	v_mfma_f32_16x16x32_bf16 v[32:35], v[206:209], v[242:245], v[32:35]
	v_mfma_f32_16x16x32_bf16 v[28:31], v[210:213], v[242:245], v[28:31]
	v_mfma_f32_16x16x32_bf16 v[24:27], v[214:217], v[242:245], v[24:27]
	ds_read_b128 v[226:229], v180 offset:4096
	ds_read_b128 v[230:233], v180 offset:6144
	s_add_i32 m0, s96, 0x4000
	v_lshl_add_u64 v[178:179], v[174:175], 0, s[22:23]
	global_load_lds_dwordx4 v[178:179], off
	s_waitcnt lgkmcnt(8)
	v_mfma_f32_16x16x32_bf16 v[20:23], v[202:205], v[246:249], v[20:23]
	v_mfma_f32_16x16x32_bf16 v[16:19], v[206:209], v[246:249], v[16:19]
	v_mfma_f32_16x16x32_bf16 v[12:15], v[210:213], v[246:249], v[12:15]
	v_mfma_f32_16x16x32_bf16 v[8:11], v[214:217], v[246:249], v[8:11]
	ds_read_b128 v[234:237], v180 offset:16384
	s_add_i32 m0, s96, 0x6000
	v_lshl_add_u64 v[178:179], v[174:175], 0, s[22:23]
	v_lshl_add_u64 v[178:179], v[178:179], 0, s[62:63]
	global_load_lds_dwordx4 v[178:179], off
	s_mov_b32 s24, 0
.Lp6_loop:
	s_waitcnt lgkmcnt(4)
	v_mfma_f32_16x16x32_bf16 v[132:135], v[186:189], v[218:221], v[132:135]
	v_mfma_f32_16x16x32_bf16 v[124:127], v[190:193], v[218:221], v[124:127]
	v_mfma_f32_16x16x32_bf16 v[128:131], v[194:197], v[218:221], v[128:131]
	v_mfma_f32_16x16x32_bf16 v[120:123], v[198:201], v[218:221], v[120:123]
	ds_read_b128 v[238:241], v180 offset:18432
	ds_read_b128 v[202:205], v181 offset:33792
	s_add_i32 m0, s96, 0x8000
	v_lshl_add_u64 v[178:179], v[172:173], 0, s[22:23]
	global_load_lds_dwordx4 v[178:179], off
	s_waitcnt lgkmcnt(5)
	v_mfma_f32_16x16x32_bf16 v[116:119], v[186:189], v[222:225], v[116:119]
	v_mfma_f32_16x16x32_bf16 v[108:111], v[190:193], v[222:225], v[108:111]
	v_mfma_f32_16x16x32_bf16 v[112:115], v[194:197], v[222:225], v[112:115]
	v_mfma_f32_16x16x32_bf16 v[104:107], v[198:201], v[222:225], v[104:107]
	ds_read_b128 v[242:245], v180 offset:20480
	ds_read_b128 v[206:209], v181 offset:35840
	s_add_i32 m0, s96, 0xa000
	v_lshl_add_u64 v[178:179], v[172:173], 0, s[22:23]
	v_lshl_add_u64 v[178:179], v[178:179], 0, s[62:63]
	global_load_lds_dwordx4 v[178:179], off
	s_waitcnt lgkmcnt(6)
	v_mfma_f32_16x16x32_bf16 v[100:103], v[186:189], v[226:229], v[100:103]
	v_mfma_f32_16x16x32_bf16 v[92:95], v[190:193], v[226:229], v[92:95]
	v_mfma_f32_16x16x32_bf16 v[96:99], v[194:197], v[226:229], v[96:99]
	v_mfma_f32_16x16x32_bf16 v[88:91], v[198:201], v[226:229], v[88:91]
	ds_read_b128 v[246:249], v180 offset:22528
	ds_read_b128 v[210:213], v181 offset:50176
	s_add_i32 m0, s96, 0xc000
	v_lshl_add_u64 v[178:179], v[176:177], 0, s[22:23]
	global_load_lds_dwordx4 v[178:179], off
	s_waitcnt lgkmcnt(7)
	v_mfma_f32_16x16x32_bf16 v[84:87], v[186:189], v[230:233], v[84:87]
	v_mfma_f32_16x16x32_bf16 v[76:79], v[190:193], v[230:233], v[76:79]
	v_mfma_f32_16x16x32_bf16 v[80:83], v[194:197], v[230:233], v[80:83]
	v_mfma_f32_16x16x32_bf16 v[72:75], v[198:201], v[230:233], v[72:75]
	ds_read_b128 v[218:221], v180 offset:1024
	ds_read_b128 v[214:217], v181 offset:52224
	s_add_i32 m0, s96, 0xe000
	v_lshl_add_u64 v[178:179], v[176:177], 0, s[22:23]
	v_lshl_add_u64 v[178:179], v[178:179], 0, s[62:63]
	global_load_lds_dwordx4 v[178:179], off
	s_add_u32 s22, s22, 0x80
	s_waitcnt lgkmcnt(8)
	v_mfma_f32_16x16x32_bf16 v[68:71], v[186:189], v[234:237], v[68:71]
	v_mfma_f32_16x16x32_bf16 v[64:67], v[190:193], v[234:237], v[64:67]
	v_mfma_f32_16x16x32_bf16 v[60:63], v[194:197], v[234:237], v[60:63]
	v_mfma_f32_16x16x32_bf16 v[56:59], v[198:201], v[234:237], v[56:59]
	ds_read_b128 v[222:225], v180 offset:3072
	s_waitcnt lgkmcnt(8)
	v_mfma_f32_16x16x32_bf16 v[52:55], v[186:189], v[238:241], v[52:55]
	v_mfma_f32_16x16x32_bf16 v[48:51], v[190:193], v[238:241], v[48:51]
	v_mfma_f32_16x16x32_bf16 v[44:47], v[194:197], v[238:241], v[44:47]
	v_mfma_f32_16x16x32_bf16 v[40:43], v[198:201], v[238:241], v[40:43]
	ds_read_b128 v[226:229], v180 offset:5120
	s_waitcnt lgkmcnt(7)
	v_mfma_f32_16x16x32_bf16 v[36:39], v[186:189], v[242:245], v[36:39]
	v_mfma_f32_16x16x32_bf16 v[32:35], v[190:193], v[242:245], v[32:35]
	v_mfma_f32_16x16x32_bf16 v[28:31], v[194:197], v[242:245], v[28:31]
	v_mfma_f32_16x16x32_bf16 v[24:27], v[198:201], v[242:245], v[24:27]
	ds_read_b128 v[230:233], v180 offset:7168
	s_waitcnt lgkmcnt(6)
	v_mfma_f32_16x16x32_bf16 v[20:23], v[186:189], v[246:249], v[20:23]
	v_mfma_f32_16x16x32_bf16 v[16:19], v[190:193], v[246:249], v[16:19]
	v_mfma_f32_16x16x32_bf16 v[12:15], v[194:197], v[246:249], v[12:15]
	v_mfma_f32_16x16x32_bf16 v[8:11], v[198:201], v[246:249], v[8:11]
	ds_read_b128 v[234:237], v180 offset:17408
	s_waitcnt lgkmcnt(4)
; template <int EPI> ...
;     ...
;       for (int t0_ = 0; t0_ < nt - 2; t0_ += 2) {
;         if constexpr (EPI == EPI_M0) {
;           if (t0_ == 8) {
;             int tid_s = tid;
;             asm volatile("" : "+v"(tid_s));
;             const int wid = tid_s >> 6, lane = tid_s & 63, wr = wid >> 2, wc = wid & 3, fr = lane & 15, fq = lane >> 4;
;             char* wsn = shm + 131072 + wid * 4096;
;             u16* sout = p.hbuf() + (long)(pm * 256 + wr * 128 + (lane >> 3)) * DM + pn * 256 + wc * 64 + (lane & 7) * 8;
; #pragma unroll
;             for (int qd = 0; qd < 4; ++qd) {
; #pragma unroll
;               for (int mm = 0; mm < 2; ++mm)
; #pragma unroll
;                 for (int n = 0; n < 4; ++n) {
;                   const f32x4 v = acc[qd * 2 + mm][n];
;                   u32x2 o = {pack2(v[0], v[1]), pack2(v[2], v[3])};
;                   *(u32x2*)(wsn + (mm * 16 + fr) * 128 + (((n * 2 + (fq >> 1)) ^ (fr & 7)) << 4) + (fq & 1) * 8) = o;
;                 }
;               asm volatile("s_waitcnt lgkmcnt(0)" ::: "memory");
; #pragma unroll
;               for (int i = 0; i < 4; ++i) {
;                 const u32x4 d = *(const u32x4*)(wsn + (i * 8 + (lane >> 3)) * 128 + (((lane & 7) ^ ((lane >> 3) & 7)) << 4));
;                 *(u32x4*)(sout + (long)(qd * 32 + i * 8) * DM) = d;
;               }
;               asm volatile("s_waitcnt lgkmcnt(0)" ::: "memory");
;             }
;           }
;         }
;         int t = t0_;
;         asm volatile("" : "+s"(t));
;         LDB8(B0, 0, 0); SCHED8; LDA8(At, 0, 0); STAGE_A(1, 1, Ab, t + 1);
;         WAIT_L(8); BAR8; WAIT_L(0); MMA8(0, 0, At, B0); BAR8; SCHED8;
;         LDB8(B1, 0, 1); STAGE_Bm(0, 0, Bb, t + 2);
;         BAR8; WAIT_L(0); MMA8(0, 1, At, B1); BAR8;
;         LDA8(At, 0, 1); STAGE_A(0, 0, Ab, t + 2);
;         BAR8; WAIT_L(0); MMA8(1, 0, At, B0); BAR8; SCHED8;
;         STAGE_Bm(0, 1, Bb, t + 2);
;         WAIT_V(6); BAR8; MMA8(1, 1, At, B1); BAR8;
;         LDB8(B0, 1, 0); SCHED8; LDA8(At, 1, 0); STAGE_A(0, 1, Ab, t + 2);
;         WAIT_L(8); BAR8; WAIT_L(0); MMA8(0, 0, At, B0); BAR8; SCHED8;
;         LDB8(B1, 1, 1); STAGE_Bm(1, 0, Bb, t + 3);
;         BAR8; WAIT_L(0); MMA8(0, 1, At, B1); BAR8;
;         LDA8(At, 1, 1); STAGE_A(1, 0, Ab, t + 3);
;         BAR8; WAIT_L(0); MMA8(1, 0, At, B0); BAR8; SCHED8;
;         STAGE_Bm(1, 1, Bb, t + 3);
	v_mfma_f32_16x16x32_bf16 v[132:135], v[202:205], v[218:221], v[132:135]
	v_mfma_f32_16x16x32_bf16 v[124:127], v[206:209], v[218:221], v[124:127]
	v_mfma_f32_16x16x32_bf16 v[128:131], v[210:213], v[218:221], v[128:131]
	v_mfma_f32_16x16x32_bf16 v[120:123], v[214:217], v[218:221], v[120:123]
	ds_read_b128 v[238:241], v180 offset:19456
	s_waitcnt lgkmcnt(4)
	v_mfma_f32_16x16x32_bf16 v[116:119], v[202:205], v[222:225], v[116:119]
	v_mfma_f32_16x16x32_bf16 v[108:111], v[206:209], v[222:225], v[108:111]
	v_mfma_f32_16x16x32_bf16 v[112:115], v[210:213], v[222:225], v[112:115]
	v_mfma_f32_16x16x32_bf16 v[104:107], v[214:217], v[222:225], v[104:107]
	ds_read_b128 v[242:245], v180 offset:21504
	s_waitcnt lgkmcnt(4)
	v_mfma_f32_16x16x32_bf16 v[100:103], v[202:205], v[226:229], v[100:103]
	v_mfma_f32_16x16x32_bf16 v[92:95], v[206:209], v[226:229], v[92:95]
	v_mfma_f32_16x16x32_bf16 v[96:99], v[210:213], v[226:229], v[96:99]
	v_mfma_f32_16x16x32_bf16 v[88:91], v[214:217], v[226:229], v[88:91]
	ds_read_b128 v[246:249], v180 offset:23552
	s_waitcnt lgkmcnt(4)
	v_mfma_f32_16x16x32_bf16 v[84:87], v[202:205], v[230:233], v[84:87]
	v_mfma_f32_16x16x32_bf16 v[76:79], v[206:209], v[230:233], v[76:79]
	v_mfma_f32_16x16x32_bf16 v[80:83], v[210:213], v[230:233], v[80:83]
	v_mfma_f32_16x16x32_bf16 v[72:75], v[214:217], v[230:233], v[72:75]
	s_waitcnt vmcnt(0) lgkmcnt(0)
	s_barrier
	v_mfma_f32_16x16x32_bf16 v[68:71], v[202:205], v[234:237], v[68:71]
	v_mfma_f32_16x16x32_bf16 v[64:67], v[206:209], v[234:237], v[64:67]
	v_mfma_f32_16x16x32_bf16 v[60:63], v[210:213], v[234:237], v[60:63]
	v_mfma_f32_16x16x32_bf16 v[56:59], v[214:217], v[234:237], v[56:59]
	ds_read_b128 v[186:189], v153 offset:32768
	ds_read_b128 v[190:193], v153 offset:34816
	ds_read_b128 v[218:221], v7
	s_add_i32 m0, s96, 0x10000
	v_lshl_add_u64 v[178:179], v[170:171], 0, s[22:23]
	global_load_lds_dwordx4 v[178:179], off
	s_waitcnt lgkmcnt(5)
	v_mfma_f32_16x16x32_bf16 v[52:55], v[202:205], v[238:241], v[52:55]
	v_mfma_f32_16x16x32_bf16 v[48:51], v[206:209], v[238:241], v[48:51]
	v_mfma_f32_16x16x32_bf16 v[44:47], v[210:213], v[238:241], v[44:47]
	v_mfma_f32_16x16x32_bf16 v[40:43], v[214:217], v[238:241], v[40:43]
	ds_read_b128 v[194:197], v153 offset:49152
	ds_read_b128 v[198:201], v153 offset:51200
	ds_read_b128 v[222:225], v7 offset:2048
	s_add_i32 m0, s96, 0x12000
	v_lshl_add_u64 v[178:179], v[170:171], 0, s[22:23]
	v_lshl_add_u64 v[178:179], v[178:179], 0, s[62:63]
	global_load_lds_dwordx4 v[178:179], off
	s_waitcnt lgkmcnt(7)
	v_mfma_f32_16x16x32_bf16 v[36:39], v[202:205], v[242:245], v[36:39]
	v_mfma_f32_16x16x32_bf16 v[32:35], v[206:209], v[242:245], v[32:35]
	v_mfma_f32_16x16x32_bf16 v[28:31], v[210:213], v[242:245], v[28:31]
	v_mfma_f32_16x16x32_bf16 v[24:27], v[214:217], v[242:245], v[24:27]
	ds_read_b128 v[226:229], v7 offset:4096
	ds_read_b128 v[230:233], v7 offset:6144
	s_add_i32 m0, s96, 0x14000
	v_lshl_add_u64 v[178:179], v[174:175], 0, s[22:23]
	global_load_lds_dwordx4 v[178:179], off
	s_waitcnt lgkmcnt(8)
	v_mfma_f32_16x16x32_bf16 v[20:23], v[202:205], v[246:249], v[20:23]
	v_mfma_f32_16x16x32_bf16 v[16:19], v[206:209], v[246:249], v[16:19]
	v_mfma_f32_16x16x32_bf16 v[12:15], v[210:213], v[246:249], v[12:15]
	v_mfma_f32_16x16x32_bf16 v[8:11], v[214:217], v[246:249], v[8:11]
	ds_read_b128 v[234:237], v7 offset:16384
	s_add_i32 m0, s96, 0x16000
	v_lshl_add_u64 v[178:179], v[174:175], 0, s[22:23]
	v_lshl_add_u64 v[178:179], v[178:179], 0, s[62:63]
	global_load_lds_dwordx4 v[178:179], off
	s_waitcnt lgkmcnt(4)
	v_mfma_f32_16x16x32_bf16 v[132:135], v[186:189], v[218:221], v[132:135]
	v_mfma_f32_16x16x32_bf16 v[124:127], v[190:193], v[218:221], v[124:127]
	v_mfma_f32_16x16x32_bf16 v[128:131], v[194:197], v[218:221], v[128:131]
	v_mfma_f32_16x16x32_bf16 v[120:123], v[198:201], v[218:221], v[120:123]
	ds_read_b128 v[238:241], v7 offset:18432
	ds_read_b128 v[202:205], v153 offset:33792
	s_add_i32 m0, s96, 0x18000
	v_lshl_add_u64 v[178:179], v[172:173], 0, s[22:23]
	global_load_lds_dwordx4 v[178:179], off
	s_waitcnt lgkmcnt(5)
	v_mfma_f32_16x16x32_bf16 v[116:119], v[186:189], v[222:225], v[116:119]
	v_mfma_f32_16x16x32_bf16 v[108:111], v[190:193], v[222:225], v[108:111]
	v_mfma_f32_16x16x32_bf16 v[112:115], v[194:197], v[222:225], v[112:115]
	v_mfma_f32_16x16x32_bf16 v[104:107], v[198:201], v[222:225], v[104:107]
	ds_read_b128 v[242:245], v7 offset:20480
	ds_read_b128 v[206:209], v153 offset:35840
	s_add_i32 m0, s96, 0x1a000
	v_lshl_add_u64 v[178:179], v[172:173], 0, s[22:23]
	v_lshl_add_u64 v[178:179], v[178:179], 0, s[62:63]
	global_load_lds_dwordx4 v[178:179], off
	s_waitcnt lgkmcnt(6)
	v_mfma_f32_16x16x32_bf16 v[100:103], v[186:189], v[226:229], v[100:103]
	v_mfma_f32_16x16x32_bf16 v[92:95], v[190:193], v[226:229], v[92:95]
	v_mfma_f32_16x16x32_bf16 v[96:99], v[194:197], v[226:229], v[96:99]
	v_mfma_f32_16x16x32_bf16 v[88:91], v[198:201], v[226:229], v[88:91]
	ds_read_b128 v[246:249], v7 offset:22528
	ds_read_b128 v[210:213], v153 offset:50176
	s_add_i32 m0, s96, 0x1c000
	v_lshl_add_u64 v[178:179], v[176:177], 0, s[22:23]
	global_load_lds_dwordx4 v[178:179], off
	s_waitcnt lgkmcnt(7)
	v_mfma_f32_16x16x32_bf16 v[84:87], v[186:189], v[230:233], v[84:87]
	v_mfma_f32_16x16x32_bf16 v[76:79], v[190:193], v[230:233], v[76:79]
	v_mfma_f32_16x16x32_bf16 v[80:83], v[194:197], v[230:233], v[80:83]
	v_mfma_f32_16x16x32_bf16 v[72:75], v[198:201], v[230:233], v[72:75]
	ds_read_b128 v[218:221], v7 offset:1024
	ds_read_b128 v[214:217], v153 offset:52224
	s_add_i32 m0, s96, 0x1e000
	v_lshl_add_u64 v[178:179], v[176:177], 0, s[22:23]
	v_lshl_add_u64 v[178:179], v[178:179], 0, s[62:63]
	global_load_lds_dwordx4 v[178:179], off
	s_add_u32 s22, s22, 0x80
	s_waitcnt lgkmcnt(8)
; #define WAIT_V(n) asm volatile("s_waitcnt vmcnt(%0)" ::"n"(n) : "memory")
; #define LDA8(dst, b, h)                                                                                              \
;   _Pragma("unroll") for (int m_ = 0; m_ < 4; ++m_) _Pragma("unroll") for (int k_ = 0; k_ < 2; ++k_)                  \
;     dst[m_][k_] = *(const bf16x8*)(shm + SLOT_A(b, h) + abase8 + m_ * 2048 + k_ * 1024)
; #define LDB8(dst, b, h)                                                                                              \
;   _Pragma("unroll") for (int n_ = 0; n_ < 2; ++n_) _Pragma("unroll") for (int k_ = 0; k_ < 2; ++k_)                  \
;     dst[n_][k_] = *(const bf16x8*)(shm + SLOT_B(b, h) + bbase8 + n_ * 2048 + k_ * 1024)
; #define WAIT_L(n) asm volatile("s_waitcnt lgkmcnt(%0)" ::"n"(n) : "memory")
; #define BAR8 __builtin_amdgcn_s_barrier()
; #define SCHED8 __builtin_amdgcn_sched_barrier(0)
; template <int EPI> ...
;     ...
;         LDB8(B0, 0, 0); SCHED8; LDA8(At, 0, 0); STAGE_A(1, 1, Ab, t + 1);
;         WAIT_L(8); BAR8; WAIT_L(0); MMA8(0, 0, At, B0); BAR8; SCHED8;
;         LDB8(B1, 0, 1); STAGE_Bm(0, 0, Bb, t + 2);
;         BAR8; WAIT_L(0); MMA8(0, 1, At, B1); BAR8;
;         LDA8(At, 0, 1); STAGE_A(0, 0, Ab, t + 2);
;         BAR8; WAIT_L(0); MMA8(1, 0, At, B0); BAR8; SCHED8;
;         STAGE_Bm(0, 1, Bb, t + 2);
;         WAIT_V(6); BAR8; MMA8(1, 1, At, B1); BAR8;
;         LDB8(B0, 1, 0); SCHED8; LDA8(At, 1, 0); STAGE_A(0, 1, Ab, t + 2);
;         WAIT_L(8); BAR8; WAIT_L(0); MMA8(0, 0, At, B0); BAR8; SCHED8;
;         LDB8(B1, 1, 1); STAGE_Bm(1, 0, Bb, t + 3);
;         BAR8; WAIT_L(0); MMA8(0, 1, At, B1); BAR8;
;         LDA8(At, 1, 1); STAGE_A(1, 0, Ab, t + 3);
;         BAR8; WAIT_L(0); MMA8(1, 0, At, B0); BAR8; SCHED8;
;         STAGE_Bm(1, 1, Bb, t + 3);
;         WAIT_V(6); BAR8; MMA8(1, 1, At, B1); BAR8;
;       }
	v_mfma_f32_16x16x32_bf16 v[68:71], v[186:189], v[234:237], v[68:71]
	v_mfma_f32_16x16x32_bf16 v[64:67], v[190:193], v[234:237], v[64:67]
	v_mfma_f32_16x16x32_bf16 v[60:63], v[194:197], v[234:237], v[60:63]
	v_mfma_f32_16x16x32_bf16 v[56:59], v[198:201], v[234:237], v[56:59]
	ds_read_b128 v[222:225], v7 offset:3072
	s_waitcnt lgkmcnt(8)
	v_mfma_f32_16x16x32_bf16 v[52:55], v[186:189], v[238:241], v[52:55]
	v_mfma_f32_16x16x32_bf16 v[48:51], v[190:193], v[238:241], v[48:51]
	v_mfma_f32_16x16x32_bf16 v[44:47], v[194:197], v[238:241], v[44:47]
	v_mfma_f32_16x16x32_bf16 v[40:43], v[198:201], v[238:241], v[40:43]
	ds_read_b128 v[226:229], v7 offset:5120
	s_waitcnt lgkmcnt(7)
	v_mfma_f32_16x16x32_bf16 v[36:39], v[186:189], v[242:245], v[36:39]
	v_mfma_f32_16x16x32_bf16 v[32:35], v[190:193], v[242:245], v[32:35]
	v_mfma_f32_16x16x32_bf16 v[28:31], v[194:197], v[242:245], v[28:31]
	v_mfma_f32_16x16x32_bf16 v[24:27], v[198:201], v[242:245], v[24:27]
	ds_read_b128 v[230:233], v7 offset:7168
	s_waitcnt lgkmcnt(6)
	v_mfma_f32_16x16x32_bf16 v[20:23], v[186:189], v[246:249], v[20:23]
	v_mfma_f32_16x16x32_bf16 v[16:19], v[190:193], v[246:249], v[16:19]
	v_mfma_f32_16x16x32_bf16 v[12:15], v[194:197], v[246:249], v[12:15]
	v_mfma_f32_16x16x32_bf16 v[8:11], v[198:201], v[246:249], v[8:11]
	ds_read_b128 v[234:237], v7 offset:17408
	s_waitcnt lgkmcnt(4)
	v_mfma_f32_16x16x32_bf16 v[132:135], v[202:205], v[218:221], v[132:135]
	v_mfma_f32_16x16x32_bf16 v[124:127], v[206:209], v[218:221], v[124:127]
	v_mfma_f32_16x16x32_bf16 v[128:131], v[210:213], v[218:221], v[128:131]
	v_mfma_f32_16x16x32_bf16 v[120:123], v[214:217], v[218:221], v[120:123]
	ds_read_b128 v[238:241], v7 offset:19456
	s_waitcnt lgkmcnt(4)
	v_mfma_f32_16x16x32_bf16 v[116:119], v[202:205], v[222:225], v[116:119]
	v_mfma_f32_16x16x32_bf16 v[108:111], v[206:209], v[222:225], v[108:111]
	v_mfma_f32_16x16x32_bf16 v[112:115], v[210:213], v[222:225], v[112:115]
	v_mfma_f32_16x16x32_bf16 v[104:107], v[214:217], v[222:225], v[104:107]
	ds_read_b128 v[242:245], v7 offset:21504
	s_waitcnt lgkmcnt(4)
	v_mfma_f32_16x16x32_bf16 v[100:103], v[202:205], v[226:229], v[100:103]
	v_mfma_f32_16x16x32_bf16 v[92:95], v[206:209], v[226:229], v[92:95]
	v_mfma_f32_16x16x32_bf16 v[96:99], v[210:213], v[226:229], v[96:99]
	v_mfma_f32_16x16x32_bf16 v[88:91], v[214:217], v[226:229], v[88:91]
	ds_read_b128 v[246:249], v7 offset:23552
	s_waitcnt lgkmcnt(4)
	v_mfma_f32_16x16x32_bf16 v[84:87], v[202:205], v[230:233], v[84:87]
	v_mfma_f32_16x16x32_bf16 v[76:79], v[206:209], v[230:233], v[76:79]
	v_mfma_f32_16x16x32_bf16 v[80:83], v[210:213], v[230:233], v[80:83]
	v_mfma_f32_16x16x32_bf16 v[72:75], v[214:217], v[230:233], v[72:75]
	s_waitcnt vmcnt(0) lgkmcnt(0)
	s_barrier
	v_mfma_f32_16x16x32_bf16 v[68:71], v[202:205], v[234:237], v[68:71]
	v_mfma_f32_16x16x32_bf16 v[64:67], v[206:209], v[234:237], v[64:67]
	v_mfma_f32_16x16x32_bf16 v[60:63], v[210:213], v[234:237], v[60:63]
	v_mfma_f32_16x16x32_bf16 v[56:59], v[214:217], v[234:237], v[56:59]
	ds_read_b128 v[186:189], v181 offset:32768
	ds_read_b128 v[190:193], v181 offset:34816
	ds_read_b128 v[218:221], v180
	s_cmp_eq_u32 s24, 6
	s_cbranch_scc1 .Lp6_alt1
	s_mov_b32 m0, s96
	v_lshl_add_u64 v[178:179], v[170:171], 0, s[22:23]
	global_load_lds_dwordx4 v[178:179], off
	s_branch .Lp6_dn2
.Lp6_alt1:
	s_cmp_lg_u64 s[20:21], 0
	s_cbranch_scc0 .Lp6_dn2
	s_mov_b32 m0, s96
	s_nop 0
	global_load_lds_dwordx4 v[156:157], off
.Lp6_dn2:
	s_waitcnt lgkmcnt(5)
	v_mfma_f32_16x16x32_bf16 v[52:55], v[202:205], v[238:241], v[52:55]
	v_mfma_f32_16x16x32_bf16 v[48:51], v[206:209], v[238:241], v[48:51]
	v_mfma_f32_16x16x32_bf16 v[44:47], v[210:213], v[238:241], v[44:47]
	v_mfma_f32_16x16x32_bf16 v[40:43], v[214:217], v[238:241], v[40:43]
	ds_read_b128 v[194:197], v181 offset:49152
	ds_read_b128 v[198:201], v181 offset:51200
	ds_read_b128 v[222:225], v180 offset:2048
	s_cmp_eq_u32 s24, 6
	s_cbranch_scc1 .Lp6_alt3
	s_add_i32 m0, s96, 0x2000
	v_lshl_add_u64 v[178:179], v[170:171], 0, s[22:23]
	v_lshl_add_u64 v[178:179], v[178:179], 0, s[62:63]
	global_load_lds_dwordx4 v[178:179], off
	s_branch .Lp6_dn4
.Lp6_alt3:
	s_cmp_lg_u64 s[20:21], 0
	s_cbranch_scc0 .Lp6_dn4
	s_add_i32 m0, s96, 0x2000
	v_lshl_add_u64 v[178:179], v[156:157], 0, s[62:63]
	global_load_lds_dwordx4 v[178:179], off
.Lp6_dn4:
	s_waitcnt lgkmcnt(7)
	v_mfma_f32_16x16x32_bf16 v[36:39], v[202:205], v[242:245], v[36:39]
	v_mfma_f32_16x16x32_bf16 v[32:35], v[206:209], v[242:245], v[32:35]
	v_mfma_f32_16x16x32_bf16 v[28:31], v[210:213], v[242:245], v[28:31]
	v_mfma_f32_16x16x32_bf16 v[24:27], v[214:217], v[242:245], v[24:27]
	ds_read_b128 v[226:229], v180 offset:4096
	ds_read_b128 v[230:233], v180 offset:6144
	s_cmp_eq_u32 s24, 6
	s_cbranch_scc1 .Lp6_alt5
	s_add_i32 m0, s96, 0x4000
	v_lshl_add_u64 v[178:179], v[174:175], 0, s[22:23]
	global_load_lds_dwordx4 v[178:179], off
	s_branch .Lp6_dn6
.Lp6_alt5:
	s_cmp_lg_u64 s[20:21], 0
	s_cbranch_scc0 .Lp6_dn6
	s_add_i32 m0, s96, 0x4000
	s_nop 0
	global_load_lds_dwordx4 v[182:183], off
.Lp6_dn6:
	s_waitcnt lgkmcnt(8)
	v_mfma_f32_16x16x32_bf16 v[20:23], v[202:205], v[246:249], v[20:23]
	v_mfma_f32_16x16x32_bf16 v[16:19], v[206:209], v[246:249], v[16:19]
	v_mfma_f32_16x16x32_bf16 v[12:15], v[210:213], v[246:249], v[12:15]
	v_mfma_f32_16x16x32_bf16 v[8:11], v[214:217], v[246:249], v[8:11]
	ds_read_b128 v[234:237], v180 offset:16384
	s_cmp_eq_u32 s24, 6
	s_cbranch_scc1 .Lp6_alt7
	s_add_i32 m0, s96, 0x6000
	v_lshl_add_u64 v[178:179], v[174:175], 0, s[22:23]
	v_lshl_add_u64 v[178:179], v[178:179], 0, s[62:63]
	global_load_lds_dwordx4 v[178:179], off
	s_branch .Lp6_dn8
; #define WAIT_V(n) asm volatile("s_waitcnt vmcnt(%0)" ::"n"(n) : "memory")
; #define LDA8(dst, b, h)                                                                                              \
;   _Pragma("unroll") for (int m_ = 0; m_ < 4; ++m_) _Pragma("unroll") for (int k_ = 0; k_ < 2; ++k_)                  \
;     dst[m_][k_] = *(const bf16x8*)(shm + SLOT_A(b, h) + abase8 + m_ * 2048 + k_ * 1024)
; #define LDB8(dst, b, h)                                                                                              \
;   _Pragma("unroll") for (int n_ = 0; n_ < 2; ++n_) _Pragma("unroll") for (int k_ = 0; k_ < 2; ++k_)                  \
;     dst[n_][k_] = *(const bf16x8*)(shm + SLOT_B(b, h) + bbase8 + n_ * 2048 + k_ * 1024)
; #define WAIT_L(n) asm volatile("s_waitcnt lgkmcnt(%0)" ::"n"(n) : "memory")
; #define BAR8 __builtin_amdgcn_s_barrier()
; template <int EPI> ...
;     ...
;       }
;       {
;         LDB8(B0, 0, 0); LDA8(At, 0, 0); STAGE_A(1, 1, Ab, nt - 1);
;         BAR8; WAIT_L(0); MMA8(0, 0, At, B0); BAR8;
;         LDB8(B1, 0, 1); BAR8; WAIT_L(0); MMA8(0, 1, At, B1); BAR8;
;         LDA8(At, 0, 1); WAIT_V(4); BAR8; WAIT_L(0); MMA8(1, 0, At, B0); MMA8(1, 1, At, B1); BAR8;
;       }
;       {
;         LDB8(B0, 1, 0); LDA8(At, 1, 0); WAIT_V(2); BAR8; WAIT_L(0); MMA8(0, 0, At, B0); BAR8;
;         LDB8(B1, 1, 1); WAIT_V(0); BAR8; WAIT_L(0); MMA8(0, 1, At, B1); BAR8;
;         LDA8(At, 1, 1); BAR8; WAIT_L(0); MMA8(1, 0, At, B0); MMA8(1, 1, At, B1); BAR8;
;       }
;       if (wr == 0) BAR8;
;     }
;     float rs[8];
.Lp6_alt7:
	s_cmp_lg_u64 s[20:21], 0
	s_cbranch_scc0 .Lp6_dn8
	s_add_i32 m0, s96, 0x6000
	v_lshl_add_u64 v[178:179], v[182:183], 0, s[62:63]
	global_load_lds_dwordx4 v[178:179], off
.Lp6_dn8:
	s_add_u32 s24, s24, 1
	s_cmp_lt_u32 s24, 7
	s_cbranch_scc1 .Lp6_loop
	s_waitcnt lgkmcnt(4)
	v_mfma_f32_16x16x32_bf16 v[132:135], v[186:189], v[218:221], v[132:135]
	v_mfma_f32_16x16x32_bf16 v[124:127], v[190:193], v[218:221], v[124:127]
	v_mfma_f32_16x16x32_bf16 v[128:131], v[194:197], v[218:221], v[128:131]
	v_mfma_f32_16x16x32_bf16 v[120:123], v[198:201], v[218:221], v[120:123]
	s_lshl_b32 s22, s93, 8
	v_add_u32_e32 v136, s22, v154
	v_ashrrev_i32_e32 v137, 31, v136
	v_lshl_add_u64 v[136:137], v[136:137], 3, s[12:13]
	global_load_dwordx2 v[150:151], v[136:137], off
	global_load_dwordx2 v[148:149], v[136:137], off offset:128
	global_load_dwordx2 v[146:147], v[136:137], off offset:256
	global_load_dwordx2 v[144:145], v[136:137], off offset:384
	global_load_dwordx2 v[142:143], v[136:137], off offset:512
	global_load_dwordx2 v[140:141], v[136:137], off offset:640
	global_load_dwordx2 v[138:139], v[136:137], off offset:768
	s_nop 0
	global_load_dwordx2 v[136:137], v[136:137], off offset:896
	ds_read_b128 v[238:241], v180 offset:18432
	ds_read_b128 v[202:205], v181 offset:33792
	s_cmp_lg_u64 s[20:21], 0
	s_cbranch_scc0 .Lp6_dn9
	s_add_i32 m0, s96, 0x8000
	s_nop 0
	global_load_lds_dwordx4 v[158:159], off
.Lp6_dn9:
	s_waitcnt lgkmcnt(5)
	v_mfma_f32_16x16x32_bf16 v[116:119], v[186:189], v[222:225], v[116:119]
	v_mfma_f32_16x16x32_bf16 v[108:111], v[190:193], v[222:225], v[108:111]
	v_mfma_f32_16x16x32_bf16 v[112:115], v[194:197], v[222:225], v[112:115]
	v_mfma_f32_16x16x32_bf16 v[104:107], v[198:201], v[222:225], v[104:107]
	ds_read_b128 v[242:245], v180 offset:20480
	ds_read_b128 v[206:209], v181 offset:35840
	s_cmp_lg_u64 s[20:21], 0
	s_cbranch_scc0 .Lp6_dn10
	s_add_i32 m0, s96, 0xa000
	v_lshl_add_u64 v[178:179], v[158:159], 0, s[62:63]
	global_load_lds_dwordx4 v[178:179], off
.Lp6_dn10:
	s_waitcnt lgkmcnt(6)
	v_mfma_f32_16x16x32_bf16 v[100:103], v[186:189], v[226:229], v[100:103]
	v_mfma_f32_16x16x32_bf16 v[92:95], v[190:193], v[226:229], v[92:95]
	v_mfma_f32_16x16x32_bf16 v[96:99], v[194:197], v[226:229], v[96:99]
	v_mfma_f32_16x16x32_bf16 v[88:91], v[198:201], v[226:229], v[88:91]
	ds_read_b128 v[246:249], v180 offset:22528
	ds_read_b128 v[210:213], v181 offset:50176
	s_cmp_lg_u64 s[20:21], 0
	s_cbranch_scc0 .Lp6_dn11
	s_add_i32 m0, s96, 0xc000
	s_nop 0
	global_load_lds_dwordx4 v[250:251], off
.Lp6_dn11:
	s_waitcnt lgkmcnt(7)
	v_mfma_f32_16x16x32_bf16 v[84:87], v[186:189], v[230:233], v[84:87]
	v_mfma_f32_16x16x32_bf16 v[76:79], v[190:193], v[230:233], v[76:79]
	v_mfma_f32_16x16x32_bf16 v[80:83], v[194:197], v[230:233], v[80:83]
	v_mfma_f32_16x16x32_bf16 v[72:75], v[198:201], v[230:233], v[72:75]
	ds_read_b128 v[218:221], v180 offset:1024
	ds_read_b128 v[214:217], v181 offset:52224
	s_cmp_lg_u64 s[20:21], 0
	s_cbranch_scc0 .Lp6_dn12
	s_add_i32 m0, s96, 0xe000
	v_lshl_add_u64 v[178:179], v[250:251], 0, s[62:63]
	global_load_lds_dwordx4 v[178:179], off
; #define WAIT_V(n) asm volatile("s_waitcnt vmcnt(%0)" ::"n"(n) : "memory")
; #define GLDS_STAGE(Ap, Bp, buf, kt)                                                                                  \
;   do {                                                                                                               \
;     STAGE_Bm(0, 0, Bp, 0); STAGE_A(0, 0, Ap, 0); STAGE_Bm(0, 1, Bp, 0); STAGE_A(0, 1, Ap, 0);                        \
;   } while (0)
; #define LDA8(dst, b, h)                                                                                              \
;   _Pragma("unroll") for (int m_ = 0; m_ < 4; ++m_) _Pragma("unroll") for (int k_ = 0; k_ < 2; ++k_)                  \
;     dst[m_][k_] = *(const bf16x8*)(shm + SLOT_A(b, h) + abase8 + m_ * 2048 + k_ * 1024)
; #define LDB8(dst, b, h)                                                                                              \
;   _Pragma("unroll") for (int n_ = 0; n_ < 2; ++n_) _Pragma("unroll") for (int k_ = 0; k_ < 2; ++k_)                  \
;     dst[n_][k_] = *(const bf16x8*)(shm + SLOT_B(b, h) + bbase8 + n_ * 2048 + k_ * 1024)
; #define WAIT_L(n) asm volatile("s_waitcnt lgkmcnt(%0)" ::"n"(n) : "memory")
; #define BAR8 __builtin_amdgcn_s_barrier()
; template <int EPI> ...
;     ...
;       {
;         LDB8(B0, 1, 0); LDA8(At, 1, 0); WAIT_V(2); BAR8; WAIT_L(0); MMA8(0, 0, At, B0); BAR8;
;         LDB8(B1, 1, 1); WAIT_V(0); BAR8; WAIT_L(0); MMA8(0, 1, At, B1); BAR8;
;         LDA8(At, 1, 1); BAR8; WAIT_L(0); MMA8(1, 0, At, B0); MMA8(1, 1, At, B1); BAR8;
;       }
;       if (wr == 0) BAR8;
;     }
;     float rs[8];
;     if constexpr (EPI == EPI_PROJ || EPI == EPI_RELU2) {
;       unsigned long long sqc[8];
; #pragma unroll
;       for (int m = 0; m < 8; ++m) sqc[m] = ssq_in[pm * 256 + wr * 128 + fr + m * 16];
; #pragma unroll
;       for (int m = 0; m < 8; ++m) rs[m] = rsqrtf((float)sqc[m] * SSQ_UNFIX + 1e-6f);
;       if (have2) GLDS_STAGE(Ab2, Bb2, 0, 0);
.Lp6_dn12:
	s_waitcnt lgkmcnt(8)
	v_mfma_f32_16x16x32_bf16 v[68:71], v[186:189], v[234:237], v[68:71]
	v_mfma_f32_16x16x32_bf16 v[64:67], v[190:193], v[234:237], v[64:67]
	v_mfma_f32_16x16x32_bf16 v[60:63], v[194:197], v[234:237], v[60:63]
	v_mfma_f32_16x16x32_bf16 v[56:59], v[198:201], v[234:237], v[56:59]
	ds_read_b128 v[222:225], v180 offset:3072
	s_waitcnt lgkmcnt(8)
	v_mfma_f32_16x16x32_bf16 v[52:55], v[186:189], v[238:241], v[52:55]
	v_mfma_f32_16x16x32_bf16 v[48:51], v[190:193], v[238:241], v[48:51]
	v_mfma_f32_16x16x32_bf16 v[44:47], v[194:197], v[238:241], v[44:47]
	v_mfma_f32_16x16x32_bf16 v[40:43], v[198:201], v[238:241], v[40:43]
	ds_read_b128 v[226:229], v180 offset:5120
	s_waitcnt lgkmcnt(7)
	v_mfma_f32_16x16x32_bf16 v[36:39], v[186:189], v[242:245], v[36:39]
	v_mfma_f32_16x16x32_bf16 v[32:35], v[190:193], v[242:245], v[32:35]
	v_mfma_f32_16x16x32_bf16 v[28:31], v[194:197], v[242:245], v[28:31]
	v_mfma_f32_16x16x32_bf16 v[24:27], v[198:201], v[242:245], v[24:27]
	ds_read_b128 v[230:233], v180 offset:7168
	s_waitcnt lgkmcnt(6)
	v_mfma_f32_16x16x32_bf16 v[20:23], v[186:189], v[246:249], v[20:23]
	v_mfma_f32_16x16x32_bf16 v[16:19], v[190:193], v[246:249], v[16:19]
	v_mfma_f32_16x16x32_bf16 v[12:15], v[194:197], v[246:249], v[12:15]
	v_mfma_f32_16x16x32_bf16 v[8:11], v[198:201], v[246:249], v[8:11]
	ds_read_b128 v[234:237], v180 offset:17408
	s_waitcnt lgkmcnt(4)
	v_mfma_f32_16x16x32_bf16 v[132:135], v[202:205], v[218:221], v[132:135]
	v_mfma_f32_16x16x32_bf16 v[124:127], v[206:209], v[218:221], v[124:127]
	v_mfma_f32_16x16x32_bf16 v[128:131], v[210:213], v[218:221], v[128:131]
	v_mfma_f32_16x16x32_bf16 v[120:123], v[214:217], v[218:221], v[120:123]
	ds_read_b128 v[238:241], v180 offset:19456
	s_waitcnt lgkmcnt(4)
	v_mfma_f32_16x16x32_bf16 v[116:119], v[202:205], v[222:225], v[116:119]
	v_mfma_f32_16x16x32_bf16 v[108:111], v[206:209], v[222:225], v[108:111]
	v_mfma_f32_16x16x32_bf16 v[112:115], v[210:213], v[222:225], v[112:115]
	v_mfma_f32_16x16x32_bf16 v[104:107], v[214:217], v[222:225], v[104:107]
	ds_read_b128 v[242:245], v180 offset:21504
	s_waitcnt lgkmcnt(4)
	v_mfma_f32_16x16x32_bf16 v[100:103], v[202:205], v[226:229], v[100:103]
	v_mfma_f32_16x16x32_bf16 v[92:95], v[206:209], v[226:229], v[92:95]
	v_mfma_f32_16x16x32_bf16 v[96:99], v[210:213], v[226:229], v[96:99]
	v_mfma_f32_16x16x32_bf16 v[88:91], v[214:217], v[226:229], v[88:91]
	ds_read_b128 v[246:249], v180 offset:23552
	s_waitcnt lgkmcnt(4)
	v_mfma_f32_16x16x32_bf16 v[84:87], v[202:205], v[230:233], v[84:87]
	v_mfma_f32_16x16x32_bf16 v[76:79], v[206:209], v[230:233], v[76:79]
	v_mfma_f32_16x16x32_bf16 v[80:83], v[210:213], v[230:233], v[80:83]
	v_mfma_f32_16x16x32_bf16 v[72:75], v[214:217], v[230:233], v[72:75]
	s_waitcnt lgkmcnt(0)
	s_barrier
	v_mfma_f32_16x16x32_bf16 v[68:71], v[202:205], v[234:237], v[68:71]
	v_mfma_f32_16x16x32_bf16 v[64:67], v[206:209], v[234:237], v[64:67]
	v_mfma_f32_16x16x32_bf16 v[60:63], v[210:213], v[234:237], v[60:63]
	v_mfma_f32_16x16x32_bf16 v[56:59], v[214:217], v[234:237], v[56:59]
	s_waitcnt lgkmcnt(2)
	v_mfma_f32_16x16x32_bf16 v[52:55], v[202:205], v[238:241], v[52:55]
	v_mfma_f32_16x16x32_bf16 v[48:51], v[206:209], v[238:241], v[48:51]
	v_mfma_f32_16x16x32_bf16 v[44:47], v[210:213], v[238:241], v[44:47]
	v_mfma_f32_16x16x32_bf16 v[40:43], v[214:217], v[238:241], v[40:43]
	s_waitcnt lgkmcnt(1)
	v_mfma_f32_16x16x32_bf16 v[36:39], v[202:205], v[242:245], v[36:39]
	v_mfma_f32_16x16x32_bf16 v[32:35], v[206:209], v[242:245], v[32:35]
	v_mfma_f32_16x16x32_bf16 v[28:31], v[210:213], v[242:245], v[28:31]
	v_mfma_f32_16x16x32_bf16 v[24:27], v[214:217], v[242:245], v[24:27]
	s_waitcnt lgkmcnt(0)
	v_mfma_f32_16x16x32_bf16 v[20:23], v[202:205], v[246:249], v[20:23]
	v_mfma_f32_16x16x32_bf16 v[16:19], v[206:209], v[246:249], v[16:19]
	v_mfma_f32_16x16x32_bf16 v[12:15], v[210:213], v[246:249], v[12:15]
	v_mfma_f32_16x16x32_bf16 v[8:11], v[214:217], v[246:249], v[8:11]
	s_waitcnt lgkmcnt(0)
	s_barrier
	s_branch .LBB0_674
